# peeled first K iterations (K|V|Q, conv in-projection, up-projection): LDS-DMA loads in scalar-base form as in the loops
# speedup vs baseline: 1.0001x; 1.0001x over previous
.LBB0_287:
	s_ashr_i32 s21, s20, 31
	s_lshl_b64 s[22:23], s[20:21], 19
	s_add_u32 s22, s80, s22
	s_addc_u32 s23, s81, s23
	s_and_b64 s[24:25], s[6:7], exec
	s_cselect_b32 s21, s23, s29
	s_cselect_b32 s36, s22, s28
	s_ashr_i32 s19, s18, 31
	s_lshl_b64 s[24:25], s[18:19], 19
	s_add_u32 s24, s40, s24
	s_addc_u32 s25, s41, s25
	s_and_b64 s[34:35], s[6:7], exec
	s_cselect_b32 s19, s25, s31
	s_cselect_b32 s37, s24, s30
	s_add_u32 s38, s30, 0x100
	s_addc_u32 s39, s31, 0
	s_add_u32 s28, s28, 0x40080
	s_addc_u32 s29, s29, 0
	s_mov_b32 s55, -2
	s_add_u32 s30, s28, 0xfffc0080
	s_addc_u32 s31, s29, -1
	s_add_i32 s56, 0, 0x10000
	s_cmp_eq_u32 s55, 12
	s_cselect_b32 s35, s21, s31
	s_cselect_b32 s34, s36, s30
	s_cselect_b32 s31, s19, s39
	s_cselect_b32 s30, s37, s38
	s_add_i32 s58, 0, 0x14000
	v_add_u32_e32 v166, s56, v147
	v_add_u32_e32 v182, s58, v147
	ds_read_b128 v[142:145], v166
	ds_read_b128 v[158:161], v166 offset:1024
	ds_read_b128 v[162:165], v166 offset:2048
	ds_read_b128 v[166:169], v166 offset:3072
	ds_read_b128 v[170:173], v182
	ds_read_b128 v[174:177], v182 offset:1024
	ds_read_b128 v[178:181], v182 offset:2048
	ds_read_b128 v[182:185], v182 offset:3072
	s_add_i32 m0, s44, 0xc000
	ds_read_b128 v[186:189], v157
	ds_read_b128 v[190:193], v157 offset:1024
	ds_read_b128 v[194:197], v157 offset:2048
	ds_read_b128 v[198:201], v157 offset:3072
	ds_read_b128 v[202:205], v157 offset:4096
	ds_read_b128 v[206:209], v157 offset:5120
	ds_read_b128 v[220:223], v157 offset:6144
	ds_read_b128 v[236:239], v157 offset:7168
	global_load_lds_dwordx4 v140, s[28:29]
	s_add_i32 m0, s44, 0xe000
	s_nop 0
	global_load_lds_dwordx4 v138, s[28:29]
	s_branch .Lpadj_0
	s_nop 0
	s_nop 0
	s_nop 0
	s_nop 0
	s_nop 0
	s_nop 0
	s_nop 0
	s_nop 0
.Lpadj_0:
	s_waitcnt vmcnt(8)
	s_waitcnt lgkmcnt(0)
	s_barrier
	v_mfma_f32_16x16x32_bf16 v[126:129], v[142:145], v[186:189], 0
	v_mfma_f32_16x16x32_bf16 v[122:125], v[162:165], v[186:189], 0
	v_mfma_f32_16x16x32_bf16 v[110:113], v[142:145], v[194:197], 0
	v_mfma_f32_16x16x32_bf16 v[106:109], v[162:165], v[194:197], 0
	v_mfma_f32_16x16x32_bf16 v[94:97], v[142:145], v[202:205], 0
	v_mfma_f32_16x16x32_bf16 v[90:93], v[162:165], v[202:205], 0
	v_mfma_f32_16x16x32_bf16 v[78:81], v[142:145], v[220:223], 0
	v_mfma_f32_16x16x32_bf16 v[74:77], v[162:165], v[220:223], 0
	v_mfma_f32_16x16x32_bf16 v[126:129], v[158:161], v[190:193], v[126:129]
	v_mfma_f32_16x16x32_bf16 v[122:125], v[166:169], v[190:193], v[122:125]
	v_mfma_f32_16x16x32_bf16 v[110:113], v[158:161], v[198:201], v[110:113]
	v_mfma_f32_16x16x32_bf16 v[106:109], v[166:169], v[198:201], v[106:109]
	v_mfma_f32_16x16x32_bf16 v[94:97], v[158:161], v[206:209], v[94:97]
	v_mfma_f32_16x16x32_bf16 v[90:93], v[166:169], v[206:209], v[90:93]
	v_mfma_f32_16x16x32_bf16 v[78:81], v[158:161], v[236:239], v[78:81]
	v_mfma_f32_16x16x32_bf16 v[74:77], v[166:169], v[236:239], v[74:77]
	v_mfma_f32_16x16x32_bf16 v[118:121], v[170:173], v[186:189], 0
	v_mfma_f32_16x16x32_bf16 v[114:117], v[178:181], v[186:189], 0
	v_mfma_f32_16x16x32_bf16 v[102:105], v[170:173], v[194:197], 0
	v_mfma_f32_16x16x32_bf16 v[98:101], v[178:181], v[194:197], 0
	v_mfma_f32_16x16x32_bf16 v[86:89], v[170:173], v[202:205], 0
	v_mfma_f32_16x16x32_bf16 v[82:85], v[178:181], v[202:205], 0
	v_mfma_f32_16x16x32_bf16 v[70:73], v[170:173], v[220:223], 0
	v_mfma_f32_16x16x32_bf16 v[66:69], v[178:181], v[220:223], 0
	v_mfma_f32_16x16x32_bf16 v[118:121], v[174:177], v[190:193], v[118:121]
	v_mfma_f32_16x16x32_bf16 v[114:117], v[182:185], v[190:193], v[114:117]
	v_mfma_f32_16x16x32_bf16 v[102:105], v[174:177], v[198:201], v[102:105]
	v_mfma_f32_16x16x32_bf16 v[98:101], v[182:185], v[198:201], v[98:101]
	v_mfma_f32_16x16x32_bf16 v[86:89], v[174:177], v[206:209], v[86:89]
	v_mfma_f32_16x16x32_bf16 v[82:85], v[182:185], v[206:209], v[82:85]
	v_mfma_f32_16x16x32_bf16 v[70:73], v[174:177], v[236:239], v[70:73]
	v_mfma_f32_16x16x32_bf16 v[66:69], v[182:185], v[236:239], v[66:69]
	s_barrier
	s_add_i32 s56, s56, s27
	s_mov_b32 m0, s56
	ds_read_b128 v[186:189], v157 offset:16384
	ds_read_b128 v[190:193], v157 offset:17408
	ds_read_b128 v[194:197], v157 offset:18432
	ds_read_b128 v[198:201], v157 offset:19456
	ds_read_b128 v[202:205], v157 offset:20480
	ds_read_b128 v[206:209], v157 offset:21504
	ds_read_b128 v[220:223], v157 offset:22528
	ds_read_b128 v[236:239], v157 offset:23552
	global_load_lds_dwordx4 v132, s[30:31]
	s_add_i32 m0, s56, 0x2000
	s_add_u32 s56, s30, 0x40000
	s_addc_u32 s57, s31, 0
	s_add_i32 s58, s58, s27
	global_load_lds_dwordx4 v136, s[30:31]
	s_mov_b32 m0, s58
	s_nop 0
	global_load_lds_dwordx4 v132, s[56:57]
	s_add_i32 m0, s58, 0x2000
	s_nop 0
	global_load_lds_dwordx4 v136, s[56:57]
	s_mov_b32 m0, s44
	s_nop 0
	global_load_lds_dwordx4 v130, s[34:35]
	s_mov_b32 m0, s45
	s_nop 0
	global_load_lds_dwordx4 v134, s[34:35]
	s_branch .Lpadj_1
	s_nop 0
	s_nop 0
	s_nop 0
	s_nop 0
	s_nop 0
	s_nop 0
	s_nop 0
	s_nop 0
	s_nop 0
	s_nop 0
	s_nop 0
	s_nop 0
	s_nop 0
	s_nop 0
.Lpadj_1:
	s_waitcnt vmcnt(8)
	s_waitcnt lgkmcnt(0)
	s_barrier
	v_mfma_f32_16x16x32_bf16 v[62:65], v[142:145], v[186:189], 0
	v_mfma_f32_16x16x32_bf16 v[58:61], v[162:165], v[186:189], 0
	v_mfma_f32_16x16x32_bf16 v[46:49], v[142:145], v[194:197], 0
	v_mfma_f32_16x16x32_bf16 v[42:45], v[162:165], v[194:197], 0
	v_mfma_f32_16x16x32_bf16 v[30:33], v[142:145], v[202:205], 0
	v_mfma_f32_16x16x32_bf16 v[26:29], v[162:165], v[202:205], 0
	v_mfma_f32_16x16x32_bf16 v[14:17], v[142:145], v[220:223], 0
	v_mfma_f32_16x16x32_bf16 v[10:13], v[162:165], v[220:223], 0
	v_mfma_f32_16x16x32_bf16 v[62:65], v[158:161], v[190:193], v[62:65]
	v_mfma_f32_16x16x32_bf16 v[58:61], v[166:169], v[190:193], v[58:61]
	v_mfma_f32_16x16x32_bf16 v[46:49], v[158:161], v[198:201], v[46:49]
	v_mfma_f32_16x16x32_bf16 v[42:45], v[166:169], v[198:201], v[42:45]
	v_mfma_f32_16x16x32_bf16 v[30:33], v[158:161], v[206:209], v[30:33]
	v_mfma_f32_16x16x32_bf16 v[26:29], v[166:169], v[206:209], v[26:29]
	v_mfma_f32_16x16x32_bf16 v[14:17], v[158:161], v[236:239], v[14:17]
	v_mfma_f32_16x16x32_bf16 v[10:13], v[166:169], v[236:239], v[10:13]
	v_mfma_f32_16x16x32_bf16 v[54:57], v[170:173], v[186:189], 0
	v_mfma_f32_16x16x32_bf16 v[50:53], v[178:181], v[186:189], 0
	v_mfma_f32_16x16x32_bf16 v[38:41], v[170:173], v[194:197], 0
	v_mfma_f32_16x16x32_bf16 v[34:37], v[178:181], v[194:197], 0
	v_mfma_f32_16x16x32_bf16 v[22:25], v[170:173], v[202:205], 0
	v_mfma_f32_16x16x32_bf16 v[18:21], v[178:181], v[202:205], 0
	v_mfma_f32_16x16x32_bf16 v[6:9], v[170:173], v[220:223], 0
	v_mfma_f32_16x16x32_bf16 v[2:5], v[178:181], v[220:223], 0
	v_mfma_f32_16x16x32_bf16 v[54:57], v[174:177], v[190:193], v[54:57]
	v_mfma_f32_16x16x32_bf16 v[50:53], v[182:185], v[190:193], v[50:53]
	v_mfma_f32_16x16x32_bf16 v[38:41], v[174:177], v[198:201], v[38:41]
	v_mfma_f32_16x16x32_bf16 v[34:37], v[182:185], v[198:201], v[34:37]
	v_mfma_f32_16x16x32_bf16 v[22:25], v[174:177], v[206:209], v[22:25]
	v_mfma_f32_16x16x32_bf16 v[18:21], v[182:185], v[206:209], v[18:21]
	v_mfma_f32_16x16x32_bf16 v[6:9], v[174:177], v[236:239], v[6:9]
	v_mfma_f32_16x16x32_bf16 v[2:5], v[182:185], v[236:239], v[2:5]
	s_barrier
	s_add_i32 s56, 0, 0x18000
	s_add_i32 s57, 0, 0x1c000
	v_add_u32_e32 v166, s56, v147
	v_add_u32_e32 v182, s57, v147
	ds_read_b128 v[142:145], v166
	ds_read_b128 v[158:161], v166 offset:1024
	ds_read_b128 v[162:165], v166 offset:2048
	ds_read_b128 v[166:169], v166 offset:3072
	ds_read_b128 v[170:173], v182
	ds_read_b128 v[174:177], v182 offset:1024
	ds_read_b128 v[178:181], v182 offset:2048
	ds_read_b128 v[182:185], v182 offset:3072
	s_add_u32 s34, s34, 0x40000
	s_addc_u32 s35, s35, 0
	s_mov_b32 m0, s43
	ds_read_b128 v[186:189], v157 offset:32768
	ds_read_b128 v[190:193], v157 offset:33792
	ds_read_b128 v[194:197], v157 offset:34816
	ds_read_b128 v[198:201], v157 offset:35840
	ds_read_b128 v[202:205], v157 offset:36864
	ds_read_b128 v[206:209], v157 offset:37888
	ds_read_b128 v[220:223], v157 offset:38912
	ds_read_b128 v[236:239], v157 offset:39936
	global_load_lds_dwordx4 v130, s[34:35]
	s_mov_b32 m0, s46
	s_nop 0
	global_load_lds_dwordx4 v134, s[34:35]
	s_branch .Lpadj_2
	s_nop 0
	s_nop 0
	s_nop 0
	s_nop 0
	s_nop 0
	s_nop 0
	s_nop 0
	s_nop 0
	s_nop 0
	s_nop 0
	s_nop 0

.LBB0_362:
	s_ashr_i32 s23, s22, 31
	s_lshl_b64 s[24:25], s[22:23], 19
	s_add_u32 s24, s80, s24
	s_addc_u32 s25, s81, s25
	s_and_b64 s[26:27], s[6:7], exec
	s_cselect_b32 s23, s25, s35
	s_cselect_b32 s39, s24, s34
	s_ashr_i32 s21, s20, 31
	s_lshl_b64 s[26:27], s[20:21], 19
	s_add_u32 s26, s45, s26
	s_addc_u32 s27, s46, s27
	s_and_b64 s[36:37], s[6:7], exec
	s_cselect_b32 s21, s27, s31
	s_cselect_b32 s40, s26, s30
	s_add_u32 s41, s30, 0x100
	s_addc_u32 s43, s31, 0
	s_add_u32 s30, s34, 0x40080
	s_addc_u32 s31, s35, 0
	s_mov_b32 s56, -2
	s_add_u32 s34, s30, 0xfffc0080
	s_addc_u32 s35, s31, -1
	s_add_i32 s57, 0, 0x10000
	s_cmp_eq_u32 s56, 12
	s_cselect_b32 s37, s23, s35
	s_cselect_b32 s36, s39, s34
	v_add_u32_e32 v146, s57, v155
	s_cselect_b32 s35, s21, s43
	s_cselect_b32 s34, s40, s41
	s_add_i32 s60, 0, 0x14000
	ds_read_b128 v[142:145], v146
	ds_read_b128 v[168:171], v146 offset:1024
	ds_read_b128 v[172:175], v146 offset:2048
	ds_read_b128 v[176:179], v146 offset:3072
	v_add_u32_e32 v146, s60, v155
	ds_read_b128 v[180:183], v146
	ds_read_b128 v[184:187], v146 offset:1024
	ds_read_b128 v[188:191], v146 offset:2048
	ds_read_b128 v[192:195], v146 offset:3072
	s_add_i32 m0, s48, 0xc000
	ds_read_b128 v[196:199], v157
	ds_read_b128 v[200:203], v157 offset:1024
	ds_read_b128 v[204:207], v157 offset:2048
	ds_read_b128 v[220:223], v157 offset:3072
	ds_read_b128 v[236:239], v157 offset:4096
	ds_read_b128 v[240:243], v157 offset:5120
	ds_read_b128 v[244:247], v157 offset:6144
	ds_read_b128 v[248:251], v157 offset:7168
	global_load_lds_dwordx4 v140, s[30:31]
	s_add_i32 m0, s48, 0xe000
	s_nop 0
	global_load_lds_dwordx4 v138, s[30:31]
	s_branch .Lpadj_8
	s_nop 0
	s_nop 0
	s_nop 0
	s_nop 0
	s_nop 0
	s_nop 0
	s_nop 0
	s_nop 0
	s_nop 0
	s_nop 0
.Lpadj_8:
	s_waitcnt vmcnt(8)
	s_waitcnt lgkmcnt(0)
	s_barrier
	v_mfma_f32_16x16x32_bf16 v[126:129], v[142:145], v[196:199], 0
	v_mfma_f32_16x16x32_bf16 v[118:121], v[172:175], v[196:199], 0
	v_mfma_f32_16x16x32_bf16 v[110:113], v[142:145], v[204:207], 0
	v_mfma_f32_16x16x32_bf16 v[102:105], v[172:175], v[204:207], 0
	v_mfma_f32_16x16x32_bf16 v[94:97], v[142:145], v[236:239], 0
	v_mfma_f32_16x16x32_bf16 v[86:89], v[172:175], v[236:239], 0
	v_mfma_f32_16x16x32_bf16 v[78:81], v[142:145], v[244:247], 0
	v_mfma_f32_16x16x32_bf16 v[70:73], v[172:175], v[244:247], 0
	v_mfma_f32_16x16x32_bf16 v[126:129], v[168:171], v[200:203], v[126:129]
	v_mfma_f32_16x16x32_bf16 v[118:121], v[176:179], v[200:203], v[118:121]
	v_mfma_f32_16x16x32_bf16 v[110:113], v[168:171], v[220:223], v[110:113]
	v_mfma_f32_16x16x32_bf16 v[102:105], v[176:179], v[220:223], v[102:105]
	v_mfma_f32_16x16x32_bf16 v[94:97], v[168:171], v[240:243], v[94:97]
	v_mfma_f32_16x16x32_bf16 v[86:89], v[176:179], v[240:243], v[86:89]
	v_mfma_f32_16x16x32_bf16 v[78:81], v[168:171], v[248:251], v[78:81]
	v_mfma_f32_16x16x32_bf16 v[70:73], v[176:179], v[248:251], v[70:73]
	v_mfma_f32_16x16x32_bf16 v[122:125], v[180:183], v[196:199], 0
	v_mfma_f32_16x16x32_bf16 v[114:117], v[188:191], v[196:199], 0
	v_mfma_f32_16x16x32_bf16 v[106:109], v[180:183], v[204:207], 0
	v_mfma_f32_16x16x32_bf16 v[98:101], v[188:191], v[204:207], 0
	v_mfma_f32_16x16x32_bf16 v[90:93], v[180:183], v[236:239], 0
	v_mfma_f32_16x16x32_bf16 v[82:85], v[188:191], v[236:239], 0
	v_mfma_f32_16x16x32_bf16 v[74:77], v[180:183], v[244:247], 0
	v_mfma_f32_16x16x32_bf16 v[66:69], v[188:191], v[244:247], 0
	v_mfma_f32_16x16x32_bf16 v[122:125], v[184:187], v[200:203], v[122:125]
	v_mfma_f32_16x16x32_bf16 v[114:117], v[192:195], v[200:203], v[114:117]
	v_mfma_f32_16x16x32_bf16 v[106:109], v[184:187], v[220:223], v[106:109]
	v_mfma_f32_16x16x32_bf16 v[98:101], v[192:195], v[220:223], v[98:101]
	v_mfma_f32_16x16x32_bf16 v[90:93], v[184:187], v[240:243], v[90:93]
	v_mfma_f32_16x16x32_bf16 v[82:85], v[192:195], v[240:243], v[82:85]
	v_mfma_f32_16x16x32_bf16 v[74:77], v[184:187], v[248:251], v[74:77]
	v_mfma_f32_16x16x32_bf16 v[66:69], v[192:195], v[248:251], v[66:69]
	s_barrier
	s_add_i32 s57, s57, s44
	v_lshl_add_u64 v[146:147], s[34:35], 0, v[134:135]
	s_mov_b32 m0, s57
	ds_read_b128 v[196:199], v157 offset:16384
	ds_read_b128 v[200:203], v157 offset:17408
	ds_read_b128 v[204:207], v157 offset:18432
	ds_read_b128 v[220:223], v157 offset:19456
	ds_read_b128 v[236:239], v157 offset:20480
	ds_read_b128 v[240:243], v157 offset:21504
	ds_read_b128 v[244:247], v157 offset:22528
	ds_read_b128 v[248:251], v157 offset:23552
	global_load_lds_dwordx4 v[146:147], off
	s_add_i32 m0, s57, 0x2000
	s_add_u32 s58, s34, 0x40000
	v_lshl_add_u64 v[208:209], s[34:35], 0, v[130:131]
	s_addc_u32 s59, s35, 0
	s_add_i32 s57, s60, s44
	global_load_lds_dwordx4 v[208:209], off
	s_mov_b32 m0, s57
	v_lshl_add_u64 v[230:231], s[36:37], 0, v[132:133]
	global_load_lds_dwordx4 v134, s[58:59]
	s_add_i32 m0, s57, 0x2000
	s_nop 0
	global_load_lds_dwordx4 v130, s[58:59]
	s_mov_b32 m0, s48
	v_lshl_add_u64 v[224:225], s[36:37], 0, v[136:137]
	global_load_lds_dwordx4 v[224:225], off
	s_mov_b32 m0, s49
	s_nop 0
	global_load_lds_dwordx4 v[230:231], off
	s_branch .Lpadj_9
	s_nop 0
	s_nop 0
	s_nop 0
	s_nop 0
	s_nop 0
	s_nop 0
	s_nop 0
	s_nop 0
.Lpadj_9:
	s_waitcnt vmcnt(8)
	s_waitcnt lgkmcnt(0)
	s_barrier
	v_mfma_f32_16x16x32_bf16 v[62:65], v[142:145], v[196:199], 0
	v_mfma_f32_16x16x32_bf16 v[54:57], v[172:175], v[196:199], 0
	v_mfma_f32_16x16x32_bf16 v[46:49], v[142:145], v[204:207], 0
	v_mfma_f32_16x16x32_bf16 v[38:41], v[172:175], v[204:207], 0
	v_mfma_f32_16x16x32_bf16 v[30:33], v[142:145], v[236:239], 0
	v_mfma_f32_16x16x32_bf16 v[22:25], v[172:175], v[236:239], 0
	v_mfma_f32_16x16x32_bf16 v[14:17], v[142:145], v[244:247], 0
	v_mfma_f32_16x16x32_bf16 v[6:9], v[172:175], v[244:247], 0
	v_mfma_f32_16x16x32_bf16 v[62:65], v[168:171], v[200:203], v[62:65]
	v_mfma_f32_16x16x32_bf16 v[54:57], v[176:179], v[200:203], v[54:57]
	v_mfma_f32_16x16x32_bf16 v[46:49], v[168:171], v[220:223], v[46:49]
	v_mfma_f32_16x16x32_bf16 v[38:41], v[176:179], v[220:223], v[38:41]
	v_mfma_f32_16x16x32_bf16 v[30:33], v[168:171], v[240:243], v[30:33]
	v_mfma_f32_16x16x32_bf16 v[22:25], v[176:179], v[240:243], v[22:25]
	v_mfma_f32_16x16x32_bf16 v[14:17], v[168:171], v[248:251], v[14:17]
	v_mfma_f32_16x16x32_bf16 v[6:9], v[176:179], v[248:251], v[6:9]
	v_mfma_f32_16x16x32_bf16 v[58:61], v[180:183], v[196:199], 0
	v_mfma_f32_16x16x32_bf16 v[50:53], v[188:191], v[196:199], 0
	v_mfma_f32_16x16x32_bf16 v[42:45], v[180:183], v[204:207], 0
	v_mfma_f32_16x16x32_bf16 v[34:37], v[188:191], v[204:207], 0
	v_mfma_f32_16x16x32_bf16 v[26:29], v[180:183], v[236:239], 0
	v_mfma_f32_16x16x32_bf16 v[18:21], v[188:191], v[236:239], 0
	v_mfma_f32_16x16x32_bf16 v[10:13], v[180:183], v[244:247], 0
	v_mfma_f32_16x16x32_bf16 v[2:5], v[188:191], v[244:247], 0
	v_mfma_f32_16x16x32_bf16 v[58:61], v[184:187], v[200:203], v[58:61]
	v_mfma_f32_16x16x32_bf16 v[50:53], v[192:195], v[200:203], v[50:53]
	v_mfma_f32_16x16x32_bf16 v[42:45], v[184:187], v[220:223], v[42:45]
	v_mfma_f32_16x16x32_bf16 v[34:37], v[192:195], v[220:223], v[34:37]
	v_mfma_f32_16x16x32_bf16 v[26:29], v[184:187], v[240:243], v[26:29]
	v_mfma_f32_16x16x32_bf16 v[18:21], v[192:195], v[240:243], v[18:21]
	v_mfma_f32_16x16x32_bf16 v[10:13], v[184:187], v[248:251], v[10:13]
	v_mfma_f32_16x16x32_bf16 v[2:5], v[192:195], v[248:251], v[2:5]
	s_barrier
	s_add_i32 s57, 0, 0x18000
	v_add_u32_e32 v164, s57, v155
	s_add_i32 s58, 0, 0x1c000
	ds_read_b128 v[142:145], v164
	ds_read_b128 v[168:171], v164 offset:1024
	ds_read_b128 v[172:175], v164 offset:2048
	ds_read_b128 v[176:179], v164 offset:3072
	v_add_u32_e32 v164, s58, v155
	ds_read_b128 v[180:183], v164
	ds_read_b128 v[184:187], v164 offset:1024
	ds_read_b128 v[188:191], v164 offset:2048
	ds_read_b128 v[192:195], v164 offset:3072
	s_add_u32 s36, s36, 0x40000
	s_addc_u32 s37, s37, 0
	s_mov_b32 m0, s50
	ds_read_b128 v[196:199], v157 offset:32768
	ds_read_b128 v[200:203], v157 offset:33792
	ds_read_b128 v[204:207], v157 offset:34816
	ds_read_b128 v[220:223], v157 offset:35840
	ds_read_b128 v[236:239], v157 offset:36864
	ds_read_b128 v[240:243], v157 offset:37888
	ds_read_b128 v[244:247], v157 offset:38912
	ds_read_b128 v[248:251], v157 offset:39936
	global_load_lds_dwordx4 v136, s[36:37]
	s_mov_b32 m0, s51
	s_nop 0
	global_load_lds_dwordx4 v132, s[36:37]
	s_branch .Lpadj_10
	s_nop 0
	s_nop 0
	s_nop 0
	s_nop 0
	s_nop 0
	s_nop 0
	s_nop 0
	s_nop 0
	s_nop 0
	s_nop 0
	s_nop 0
.Lpadj_10:
	s_waitcnt vmcnt(8)
	s_waitcnt lgkmcnt(0)
	s_barrier
	v_mfma_f32_16x16x32_bf16 v[126:129], v[142:145], v[196:199], v[126:129]
	v_mfma_f32_16x16x32_bf16 v[118:121], v[172:175], v[196:199], v[118:121]
	v_mfma_f32_16x16x32_bf16 v[110:113], v[142:145], v[204:207], v[110:113]
	v_mfma_f32_16x16x32_bf16 v[102:105], v[172:175], v[204:207], v[102:105]
	v_mfma_f32_16x16x32_bf16 v[94:97], v[142:145], v[236:239], v[94:97]
	v_mfma_f32_16x16x32_bf16 v[86:89], v[172:175], v[236:239], v[86:89]
	v_mfma_f32_16x16x32_bf16 v[78:81], v[142:145], v[244:247], v[78:81]
	v_mfma_f32_16x16x32_bf16 v[70:73], v[172:175], v[244:247], v[70:73]
	v_mfma_f32_16x16x32_bf16 v[126:129], v[168:171], v[200:203], v[126:129]
	v_mfma_f32_16x16x32_bf16 v[118:121], v[176:179], v[200:203], v[118:121]
	v_mfma_f32_16x16x32_bf16 v[110:113], v[168:171], v[220:223], v[110:113]
	v_mfma_f32_16x16x32_bf16 v[102:105], v[176:179], v[220:223], v[102:105]
	v_mfma_f32_16x16x32_bf16 v[94:97], v[168:171], v[240:243], v[94:97]
	v_mfma_f32_16x16x32_bf16 v[86:89], v[176:179], v[240:243], v[86:89]
	v_mfma_f32_16x16x32_bf16 v[78:81], v[168:171], v[248:251], v[78:81]
	v_mfma_f32_16x16x32_bf16 v[70:73], v[176:179], v[248:251], v[70:73]
	v_mfma_f32_16x16x32_bf16 v[122:125], v[180:183], v[196:199], v[122:125]
	v_mfma_f32_16x16x32_bf16 v[114:117], v[188:191], v[196:199], v[114:117]
	v_mfma_f32_16x16x32_bf16 v[106:109], v[180:183], v[204:207], v[106:109]
	v_mfma_f32_16x16x32_bf16 v[98:101], v[188:191], v[204:207], v[98:101]
	v_mfma_f32_16x16x32_bf16 v[90:93], v[180:183], v[236:239], v[90:93]
	v_mfma_f32_16x16x32_bf16 v[82:85], v[188:191], v[236:239], v[82:85]
	v_mfma_f32_16x16x32_bf16 v[74:77], v[180:183], v[244:247], v[74:77]
	v_mfma_f32_16x16x32_bf16 v[66:69], v[188:191], v[244:247], v[66:69]
	v_mfma_f32_16x16x32_bf16 v[122:125], v[184:187], v[200:203], v[122:125]
	v_mfma_f32_16x16x32_bf16 v[114:117], v[192:195], v[200:203], v[114:117]
	v_mfma_f32_16x16x32_bf16 v[106:109], v[184:187], v[220:223], v[106:109]
	v_mfma_f32_16x16x32_bf16 v[98:101], v[192:195], v[220:223], v[98:101]
	v_mfma_f32_16x16x32_bf16 v[90:93], v[184:187], v[240:243], v[90:93]
	v_mfma_f32_16x16x32_bf16 v[82:85], v[192:195], v[240:243], v[82:85]
	v_mfma_f32_16x16x32_bf16 v[74:77], v[184:187], v[248:251], v[74:77]
	v_mfma_f32_16x16x32_bf16 v[66:69], v[192:195], v[248:251], v[66:69]
	s_barrier
	s_add_i32 s36, s57, s44
	v_lshl_add_u64 v[146:147], v[146:147], 0, s[96:97]
	s_mov_b32 m0, s36
	ds_read_b128 v[196:199], v157 offset:49152
	ds_read_b128 v[200:203], v157 offset:50176
	ds_read_b128 v[204:207], v157 offset:51200
	ds_read_b128 v[220:223], v157 offset:52224
	ds_read_b128 v[236:239], v157 offset:53248
	ds_read_b128 v[240:243], v157 offset:54272
	ds_read_b128 v[244:247], v157 offset:55296
	ds_read_b128 v[248:251], v157 offset:56320
	global_load_lds_dwordx4 v[146:147], off
	s_add_i32 m0, s36, 0x2000
	s_add_u32 s34, s34, 0x40080
	v_lshl_add_u64 v[146:147], v[208:209], 0, s[96:97]
	s_addc_u32 s35, s35, 0
	s_add_i32 s36, s58, s44
	global_load_lds_dwordx4 v[146:147], off
	s_mov_b32 m0, s36
	s_nop 0
	global_load_lds_dwordx4 v134, s[34:35]
	s_add_i32 m0, s36, 0x2000
	s_nop 0
	global_load_lds_dwordx4 v130, s[34:35]
	s_mov_b32 m0, s52
	v_lshl_add_u64 v[146:147], v[224:225], 0, s[96:97]
	global_load_lds_dwordx4 v[146:147], off
	s_mov_b32 m0, s53
	v_lshl_add_u64 v[146:147], v[230:231], 0, s[96:97]
	global_load_lds_dwordx4 v[146:147], off
	s_branch .Lpadj_11
	s_nop 0
	s_nop 0
	s_nop 0
	s_nop 0
	s_nop 0
	s_nop 0
	s_nop 0
	s_nop 0

.LBB0_639:
	s_ashr_i32 s13, s12, 31
	s_lshl_b64 s[14:15], s[12:13], 19
	s_add_u32 s14, s80, s14
	s_addc_u32 s15, s81, s15
	s_and_b64 s[16:17], s[4:5], exec
	s_cselect_b32 s13, s15, s23
	s_cselect_b32 s19, s14, s22
	s_ashr_i32 s11, s10, 31
	s_lshl_b64 s[16:17], s[10:11], 19
	s_add_u32 s16, s26, s16
	s_addc_u32 s17, s27, s17
	s_and_b64 s[24:25], s[4:5], exec
	s_cselect_b32 s11, s17, s21
	s_cselect_b32 s41, s16, s20
	s_add_u32 s43, s20, 0x100
	s_addc_u32 s44, s21, 0
	s_add_u32 s20, s22, 0x40080
	s_addc_u32 s21, s23, 0
	s_mov_b32 s45, -2
	s_add_u32 s22, s20, 0xfffc0080
	s_addc_u32 s23, s21, -1
	s_add_i32 s46, 0, 0x10000
	s_cmp_eq_u32 s45, 12
	s_cselect_b32 s25, s13, s23
	s_cselect_b32 s24, s19, s22
	v_add_u32_e32 v150, s46, v159
	s_cselect_b32 s23, s11, s44
	s_cselect_b32 s22, s41, s43
	s_add_i32 s48, 0, 0x14000
	ds_read_b128 v[164:167], v150
	ds_read_b128 v[168:171], v150 offset:1024
	ds_read_b128 v[172:175], v150 offset:2048
	ds_read_b128 v[176:179], v150 offset:3072
	v_add_u32_e32 v150, s48, v159
	ds_read_b128 v[180:183], v150
	ds_read_b128 v[184:187], v150 offset:1024
	ds_read_b128 v[188:191], v150 offset:2048
	ds_read_b128 v[192:195], v150 offset:3072
	s_add_i32 m0, s30, 0xc000
	ds_read_b128 v[196:199], v162
	ds_read_b128 v[200:203], v162 offset:1024
	ds_read_b128 v[204:207], v162 offset:2048
	ds_read_b128 v[220:223], v162 offset:3072
	ds_read_b128 v[236:239], v162 offset:4096
	ds_read_b128 v[240:243], v162 offset:5120
	ds_read_b128 v[244:247], v162 offset:6144
	ds_read_b128 v[248:251], v162 offset:7168
	global_load_lds_dwordx4 v140, s[20:21]
	s_add_i32 m0, s30, 0xe000
	s_nop 0
	global_load_lds_dwordx4 v138, s[20:21]
	s_branch .Lpadj_20
	s_nop 0
	s_nop 0
	s_nop 0
	s_nop 0
	s_nop 0
	s_nop 0
	s_nop 0
	s_nop 0
	s_nop 0
	s_nop 0
	s_nop 0
	s_nop 0
.Lpadj_20:
	s_waitcnt vmcnt(8)
	s_waitcnt lgkmcnt(0)
	s_barrier
	v_mfma_f32_16x16x32_bf16 v[126:129], v[164:167], v[196:199], 0
	v_mfma_f32_16x16x32_bf16 v[122:125], v[172:175], v[196:199], 0
	v_mfma_f32_16x16x32_bf16 v[118:121], v[164:167], v[204:207], 0
	v_mfma_f32_16x16x32_bf16 v[114:117], v[172:175], v[204:207], 0
	v_mfma_f32_16x16x32_bf16 v[110:113], v[164:167], v[236:239], 0
	v_mfma_f32_16x16x32_bf16 v[106:109], v[172:175], v[236:239], 0
	v_mfma_f32_16x16x32_bf16 v[102:105], v[164:167], v[244:247], 0
	v_mfma_f32_16x16x32_bf16 v[98:101], v[172:175], v[244:247], 0
	v_mfma_f32_16x16x32_bf16 v[126:129], v[168:171], v[200:203], v[126:129]
	v_mfma_f32_16x16x32_bf16 v[122:125], v[176:179], v[200:203], v[122:125]
	v_mfma_f32_16x16x32_bf16 v[118:121], v[168:171], v[220:223], v[118:121]
	v_mfma_f32_16x16x32_bf16 v[114:117], v[176:179], v[220:223], v[114:117]
	v_mfma_f32_16x16x32_bf16 v[110:113], v[168:171], v[240:243], v[110:113]
	v_mfma_f32_16x16x32_bf16 v[106:109], v[176:179], v[240:243], v[106:109]
	v_mfma_f32_16x16x32_bf16 v[102:105], v[168:171], v[248:251], v[102:105]
	v_mfma_f32_16x16x32_bf16 v[98:101], v[176:179], v[248:251], v[98:101]
	v_mfma_f32_16x16x32_bf16 v[94:97], v[180:183], v[196:199], 0
	v_mfma_f32_16x16x32_bf16 v[90:93], v[188:191], v[196:199], 0
	v_mfma_f32_16x16x32_bf16 v[86:89], v[180:183], v[204:207], 0
	v_mfma_f32_16x16x32_bf16 v[82:85], v[188:191], v[204:207], 0
	v_mfma_f32_16x16x32_bf16 v[78:81], v[180:183], v[236:239], 0
	v_mfma_f32_16x16x32_bf16 v[74:77], v[188:191], v[236:239], 0
	v_mfma_f32_16x16x32_bf16 v[70:73], v[180:183], v[244:247], 0
	v_mfma_f32_16x16x32_bf16 v[66:69], v[188:191], v[244:247], 0
	v_mfma_f32_16x16x32_bf16 v[94:97], v[184:187], v[200:203], v[94:97]
	v_mfma_f32_16x16x32_bf16 v[90:93], v[192:195], v[200:203], v[90:93]
	v_mfma_f32_16x16x32_bf16 v[86:89], v[184:187], v[220:223], v[86:89]
	v_mfma_f32_16x16x32_bf16 v[82:85], v[192:195], v[220:223], v[82:85]
	v_mfma_f32_16x16x32_bf16 v[78:81], v[184:187], v[240:243], v[78:81]
	v_mfma_f32_16x16x32_bf16 v[74:77], v[192:195], v[240:243], v[74:77]
	v_mfma_f32_16x16x32_bf16 v[70:73], v[184:187], v[248:251], v[70:73]
	v_mfma_f32_16x16x32_bf16 v[66:69], v[192:195], v[248:251], v[66:69]
	s_barrier
	s_add_i32 s46, s46, s28
	s_mov_b32 m0, s46
	ds_read_b128 v[196:199], v162 offset:16384
	ds_read_b128 v[200:203], v162 offset:17408
	ds_read_b128 v[204:207], v162 offset:18432
	ds_read_b128 v[220:223], v162 offset:19456
	ds_read_b128 v[236:239], v162 offset:20480
	ds_read_b128 v[240:243], v162 offset:21504
	ds_read_b128 v[244:247], v162 offset:22528
	ds_read_b128 v[248:251], v162 offset:23552
	global_load_lds_dwordx4 v134, s[22:23]
	s_add_i32 m0, s46, 0x2000
	s_add_u32 s46, s22, 0x40000
	s_addc_u32 s47, s23, 0
	s_add_i32 s48, s48, s28
	global_load_lds_dwordx4 v130, s[22:23]
	s_mov_b32 m0, s48
	s_nop 0
	global_load_lds_dwordx4 v134, s[46:47]
	s_add_i32 m0, s48, 0x2000
	s_nop 0
	global_load_lds_dwordx4 v130, s[46:47]
	s_mov_b32 m0, s30
	s_nop 0
	global_load_lds_dwordx4 v136, s[24:25]
	s_mov_b32 m0, s31
	s_nop 0
	global_load_lds_dwordx4 v132, s[24:25]
	s_branch .Lpadj_21
	s_nop 0
	s_nop 0
	s_nop 0
	s_nop 0
	s_nop 0
	s_nop 0
	s_nop 0
	s_nop 0
	s_nop 0
	s_nop 0
	s_nop 0
	s_nop 0
	s_nop 0
	s_nop 0
.Lpadj_21:
	s_waitcnt vmcnt(8)
	s_waitcnt lgkmcnt(0)
	s_barrier
	v_mfma_f32_16x16x32_bf16 v[62:65], v[164:167], v[196:199], 0
	v_mfma_f32_16x16x32_bf16 v[58:61], v[172:175], v[196:199], 0
	v_mfma_f32_16x16x32_bf16 v[54:57], v[164:167], v[204:207], 0
	v_mfma_f32_16x16x32_bf16 v[50:53], v[172:175], v[204:207], 0
	v_mfma_f32_16x16x32_bf16 v[46:49], v[164:167], v[236:239], 0
	v_mfma_f32_16x16x32_bf16 v[42:45], v[172:175], v[236:239], 0
	v_mfma_f32_16x16x32_bf16 v[38:41], v[164:167], v[244:247], 0
	v_mfma_f32_16x16x32_bf16 v[34:37], v[172:175], v[244:247], 0
	v_mfma_f32_16x16x32_bf16 v[62:65], v[168:171], v[200:203], v[62:65]
	v_mfma_f32_16x16x32_bf16 v[58:61], v[176:179], v[200:203], v[58:61]
	v_mfma_f32_16x16x32_bf16 v[54:57], v[168:171], v[220:223], v[54:57]
	v_mfma_f32_16x16x32_bf16 v[50:53], v[176:179], v[220:223], v[50:53]
	v_mfma_f32_16x16x32_bf16 v[46:49], v[168:171], v[240:243], v[46:49]
	v_mfma_f32_16x16x32_bf16 v[42:45], v[176:179], v[240:243], v[42:45]
	v_mfma_f32_16x16x32_bf16 v[38:41], v[168:171], v[248:251], v[38:41]
	v_mfma_f32_16x16x32_bf16 v[34:37], v[176:179], v[248:251], v[34:37]
	v_mfma_f32_16x16x32_bf16 v[30:33], v[180:183], v[196:199], 0
	v_mfma_f32_16x16x32_bf16 v[26:29], v[188:191], v[196:199], 0
	v_mfma_f32_16x16x32_bf16 v[22:25], v[180:183], v[204:207], 0
	v_mfma_f32_16x16x32_bf16 v[18:21], v[188:191], v[204:207], 0
	v_mfma_f32_16x16x32_bf16 v[14:17], v[180:183], v[236:239], 0
	v_mfma_f32_16x16x32_bf16 v[10:13], v[188:191], v[236:239], 0
	v_mfma_f32_16x16x32_bf16 v[6:9], v[180:183], v[244:247], 0
	v_mfma_f32_16x16x32_bf16 v[2:5], v[188:191], v[244:247], 0
	v_mfma_f32_16x16x32_bf16 v[30:33], v[184:187], v[200:203], v[30:33]
	v_mfma_f32_16x16x32_bf16 v[26:29], v[192:195], v[200:203], v[26:29]
	v_mfma_f32_16x16x32_bf16 v[22:25], v[184:187], v[220:223], v[22:25]
	v_mfma_f32_16x16x32_bf16 v[18:21], v[192:195], v[220:223], v[18:21]
	v_mfma_f32_16x16x32_bf16 v[14:17], v[184:187], v[240:243], v[14:17]
	v_mfma_f32_16x16x32_bf16 v[10:13], v[192:195], v[240:243], v[10:13]
	v_mfma_f32_16x16x32_bf16 v[6:9], v[184:187], v[248:251], v[6:9]
	v_mfma_f32_16x16x32_bf16 v[2:5], v[192:195], v[248:251], v[2:5]
	s_barrier
	s_add_i32 s46, 0, 0x18000
	v_add_u32_e32 v163, s46, v159
	s_add_i32 s47, 0, 0x1c000
	ds_read_b128 v[164:167], v163
	ds_read_b128 v[168:171], v163 offset:1024
	ds_read_b128 v[172:175], v163 offset:2048
	ds_read_b128 v[176:179], v163 offset:3072
	v_add_u32_e32 v163, s47, v159
	ds_read_b128 v[180:183], v163
	ds_read_b128 v[184:187], v163 offset:1024
	ds_read_b128 v[188:191], v163 offset:2048
	ds_read_b128 v[192:195], v163 offset:3072
	s_add_u32 s24, s24, 0x40000
	s_addc_u32 s25, s25, 0
	s_mov_b32 m0, s34
	ds_read_b128 v[196:199], v162 offset:32768
	ds_read_b128 v[200:203], v162 offset:33792
	ds_read_b128 v[204:207], v162 offset:34816
	ds_read_b128 v[220:223], v162 offset:35840
	ds_read_b128 v[236:239], v162 offset:36864
	ds_read_b128 v[240:243], v162 offset:37888
	ds_read_b128 v[244:247], v162 offset:38912
	ds_read_b128 v[248:251], v162 offset:39936
	global_load_lds_dwordx4 v136, s[24:25]
	s_mov_b32 m0, s35
	s_nop 0
	global_load_lds_dwordx4 v132, s[24:25]
	s_branch .Lpadj_22
	s_nop 0
	s_nop 0
	s_nop 0
	s_nop 0
	s_nop 0
	s_nop 0
	s_nop 0
	s_nop 0
	s_nop 0
	s_nop 0
	s_nop 0
